# P3 loop: V fragments prefetched four MFMAs ahead through a six-buffer ring, one LDS wait per MFMA pair; loop bounds and the bias argument kept as running scalars
# speedup vs baseline: 1.0171x; 1.0171x over previous
.LBB0_318:
	s_or_b32 s0, s78, 31
	s_or_b32 s1, s2, 64
	s_cmp_gt_u32 s1, s0
	s_cselect_b64 s[70:71], -1, 0
	s_cmp_lg_u64 s[70:71], 0
	s_subb_u32 s82, s33, 0
	s_sub_i32 s0, s72, s2
	v_cvt_f32_i32_e32 v38, s0
	v_lshrrev_b32_e32 v35, 2, v35
	v_lshlrev_b32_e32 v45, 1, v211
	v_and_b32_e32 v44, 12, v33
	v_fma_f32 v40, v208, v38, -v207
	v_fmamk_f32 v41, v208, 0x42000000, v40
	v_add_f32_e32 v16, v40, v16
	v_add_f32_e32 v0, v41, v0
	v_exp_f32_e32 v42, v16
	v_exp_f32_e32 v43, v0
	v_add_f32_e32 v0, v40, v17
	v_add_f32_e32 v1, v41, v1
	v_exp_f32_e32 v0, v0
	v_exp_f32_e32 v16, v1
	v_add_f32_e32 v17, v43, v42
	v_mov_b32_e32 v1, v113
	v_add_f32_e32 v2, v41, v2
	v_pk_add_f32 v[38:39], v[16:17], v[0:1]
	v_add_f32_e32 v1, v40, v18
	v_pk_add_f32 v[38:39], v[38:39], v[38:39] op_sel_hi:[0,1]
	v_exp_f32_e32 v17, v2
	v_add_f32_e32 v2, v40, v19
	v_exp_f32_e32 v1, v1
	v_exp_f32_e32 v38, v2
	v_add_f32_e32 v2, v41, v3
	v_exp_f32_e32 v2, v2
	v_add_f32_e32 v3, v17, v1
	v_add_f32_e32 v4, v41, v4
	v_add_f32_e32 v6, v41, v6
	v_pk_add_f32 v[18:19], v[2:3], v[38:39]
	v_add_f32_e32 v3, v40, v20
	v_pk_add_f32 v[18:19], v[18:19], v[18:19] op_sel_hi:[0,1]
	v_exp_f32_e32 v39, v4
	v_add_f32_e32 v4, v40, v21
	v_exp_f32_e32 v3, v3
	v_exp_f32_e32 v18, v4
	v_add_f32_e32 v4, v41, v5
	v_exp_f32_e32 v4, v4
	v_or_b32_e32 v5, v34, v35
	v_lshlrev_b32_e32 v35, 8, v5
	v_add_f32_e32 v5, v39, v3
	v_pk_add_f32 v[20:21], v[4:5], v[18:19]
	v_add_f32_e32 v5, v40, v22
	v_pk_add_f32 v[20:21], v[20:21], v[20:21] op_sel_hi:[0,1]
	v_exp_f32_e32 v19, v6
	v_add_f32_e32 v6, v40, v23
	v_exp_f32_e32 v5, v5
	v_exp_f32_e32 v20, v6
	v_add_f32_e32 v6, v41, v7
	v_exp_f32_e32 v6, v6
	v_add_f32_e32 v7, v19, v5
	v_add_f32_e32 v8, v41, v8
	v_add_f32_e32 v10, v41, v10
	v_pk_add_f32 v[22:23], v[6:7], v[20:21]
	v_add_f32_e32 v7, v40, v24
	v_pk_add_f32 v[22:23], v[22:23], v[22:23] op_sel_hi:[0,1]
	v_exp_f32_e32 v21, v8
	v_add_f32_e32 v8, v40, v25
	v_exp_f32_e32 v7, v7
	v_exp_f32_e32 v22, v8
	v_add_f32_e32 v8, v41, v9
	v_exp_f32_e32 v8, v8
	v_add_f32_e32 v9, v21, v7
	v_and_b32_e32 v45, 2, v45
	v_and_b32_e32 v37, 1, v37
	v_pk_add_f32 v[24:25], v[8:9], v[22:23]
	v_add_f32_e32 v9, v40, v26
	v_pk_add_f32 v[24:25], v[24:25], v[24:25] op_sel_hi:[0,1]
	v_exp_f32_e32 v23, v10
	v_add_f32_e32 v10, v40, v27
	v_exp_f32_e32 v9, v9
	v_exp_f32_e32 v24, v10
	v_add_f32_e32 v10, v41, v11
	v_exp_f32_e32 v10, v10
	v_or3_b32 v11, v44, v45, v37
	v_lshlrev_b32_e32 v37, 4, v11
	v_add_f32_e32 v11, v23, v9
	v_pk_add_f32 v[26:27], v[10:11], v[24:25]
	v_add_f32_e32 v12, v41, v12
	v_pk_add_f32 v[26:27], v[26:27], v[26:27] op_sel_hi:[0,1]
	v_add_f32_e32 v11, v40, v28
	v_exp_f32_e32 v25, v12
	v_add_f32_e32 v12, v40, v29
	v_exp_f32_e32 v11, v11
	v_exp_f32_e32 v26, v12
	v_add_f32_e32 v12, v41, v13
	v_exp_f32_e32 v12, v12
	v_lshlrev_b32_e32 v13, 3, v33
	v_and_b32_e32 v33, 8, v13
	v_add_f32_e32 v13, v25, v11
	v_pk_add_f32 v[28:29], v[12:13], v[26:27]
	v_add_f32_e32 v14, v41, v14
	v_pk_add_f32 v[28:29], v[28:29], v[28:29] op_sel_hi:[0,1]
	v_add_f32_e32 v13, v40, v30
	v_exp_f32_e32 v27, v14
	v_add_f32_e32 v14, v40, v31
	v_exp_f32_e32 v13, v13
	v_exp_f32_e32 v28, v14
	v_add_f32_e32 v14, v41, v15
	v_exp_f32_e32 v14, v14
	v_add_f32_e32 v15, v27, v13
	v_or3_b32 v235, v37, v35, v33
	s_mov_b32 s72, 0
	v_pk_add_f32 v[30:31], v[14:15], v[28:29]
	v_cvt_pk_bf16_f32 v152, v42, v0
	v_cvt_pk_bf16_f32 v153, v1, v38
	v_cvt_pk_bf16_f32 v154, v3, v18
	v_cvt_pk_bf16_f32 v155, v5, v20
	v_cvt_pk_bf16_f32 v156, v7, v22
	s_nop 0
	v_add_f32_e32 v15, v30, v31
	v_add_f32_e32 v229, 0, v15
	v_cvt_pk_bf16_f32 v157, v9, v24
	v_cvt_pk_bf16_f32 v158, v11, v26
	v_cvt_pk_bf16_f32 v159, v13, v28
	v_cvt_pk_bf16_f32 v148, v43, v16
	v_cvt_pk_bf16_f32 v149, v17, v2
	v_cvt_pk_bf16_f32 v150, v39, v4
	v_cvt_pk_bf16_f32 v151, v19, v6
	v_cvt_pk_bf16_f32 v160, v21, v8
	v_cvt_pk_bf16_f32 v161, v23, v10
	v_cvt_pk_bf16_f32 v162, v25, v12
	v_cvt_pk_bf16_f32 v163, v27, v14
	s_cmp_lt_i32 s82, 2
	v_xor_b32_e32 v236, 0x80, v235
	v_xor_b32_e32 v234, 0xc0, v235
	s_cbranch_scc1 .LBB0_331
	s_mov_b32 s97, s83
	s_lshl_b64 s[0:1], s[96:97], 13
	v_lshl_add_u64 v[0:1], v[212:213], 0, s[0:1]
	s_mov_b64 s[0:1], 0x106000
	v_lshl_add_u64 v[218:219], v[0:1], 0, s[0:1]
	s_mov_b64 s[0:1], 0x6000
	v_lshl_add_u64 v[220:221], v[0:1], 0, s[0:1]
	s_lshl_b64 s[0:1], s[96:97], 14
	v_lshl_add_u64 v[0:1], v[214:215], 0, s[0:1]
	s_mov_b64 s[4:5], 0xc000
	v_lshl_add_u64 v[222:223], v[0:1], 0, s[4:5]
	v_lshl_add_u64 v[0:1], v[216:217], 0, s[0:1]
	v_readlane_b32 s1, v244, 25
	s_add_i32 s1, s1, s2
	v_lshl_add_u64 v[224:225], v[0:1], 0, s[4:5]
	v_add_u32_e32 v0, s1, v32
	s_lshl_b32 s0, s96, 6
	v_sub_u32_e32 v0, v0, v34
	s_add_i32 s97, s0, 0x7f
	v_subrev_u32_e32 v240, s0, v0
	s_and_b32 s0, s74, 63
	s_lshl_b32 s0, s0, 7
	v_mov_b32_e32 v0, 0
	v_mul_f32_e32 v237, 0x42000000, v208
	v_add_u32_e32 v238, 0, v36
	v_xor_b32_e32 v239, 64, v235
	s_add_i32 s73, s33, -2
	s_add_i32 s79, s77, 0x18000
	s_sub_i32 s74, 0, s0
	v_mov_b32_e32 v1, v0
	v_mov_b32_e32 v2, v0
	v_mov_b32_e32 v3, v0
	v_mov_b32_e32 v4, v0
	v_mov_b32_e32 v5, v0
	v_mov_b32_e32 v6, v0
	v_mov_b32_e32 v7, v0
	v_mov_b32_e32 v8, v0
	v_mov_b32_e32 v9, v0
	v_mov_b32_e32 v10, v0
	v_mov_b32_e32 v11, v0
	v_mov_b32_e32 v12, v0
	v_mov_b32_e32 v13, v0
	v_mov_b32_e32 v14, v0
	v_mov_b32_e32 v15, v0
	v_mov_b32_e32 v16, v0
	v_mov_b32_e32 v17, v0
	v_mov_b32_e32 v18, v0
	v_mov_b32_e32 v19, v0
	v_mov_b32_e32 v20, v0
	v_mov_b32_e32 v21, v0
	v_mov_b32_e32 v22, v0
	v_mov_b32_e32 v23, v0
	v_mov_b32_e32 v24, v0
	v_mov_b32_e32 v25, v0
	v_mov_b32_e32 v26, v0
	v_mov_b32_e32 v27, v0
	v_mov_b32_e32 v28, v0
	v_mov_b32_e32 v29, v0
	v_mov_b32_e32 v30, v0
	v_mov_b32_e32 v31, v0
	v_mov_b32_e32 v32, v0
	v_mov_b32_e32 v33, v0
	v_mov_b32_e32 v34, v0
	v_mov_b32_e32 v35, v0
	v_mov_b32_e32 v36, v0
	v_mov_b32_e32 v37, v0
	v_mov_b32_e32 v38, v0
	v_mov_b32_e32 v39, v0
	v_mov_b32_e32 v40, v0
	v_mov_b32_e32 v41, v0
	v_mov_b32_e32 v42, v0
	v_mov_b32_e32 v43, v0
	v_mov_b32_e32 v44, v0
	v_mov_b32_e32 v45, v0
	v_mov_b32_e32 v46, v0
	v_mov_b32_e32 v47, v0
	v_mov_b32_e32 v48, v0
	v_mov_b32_e32 v49, v0
	v_mov_b32_e32 v50, v0
	v_mov_b32_e32 v51, v0
	v_mov_b32_e32 v52, v0
	v_mov_b32_e32 v53, v0
	v_mov_b32_e32 v54, v0
	v_mov_b32_e32 v55, v0
	v_mov_b32_e32 v56, v0
	v_mov_b32_e32 v57, v0
	v_mov_b32_e32 v58, v0
	v_mov_b32_e32 v59, v0
	v_mov_b32_e32 v60, v0
	v_mov_b32_e32 v61, v0
	v_mov_b32_e32 v62, v0
	v_mov_b32_e32 v63, v0
	s_add_i32 s98, s33, -3
	s_add_i32 s99, s82, -1
	s_add_i32 s100, s74, s97
	s_sub_i32 s100, s100, 63
	v_mov_b32_e32 v166, v160
	v_mov_b32_e32 v167, v161
	v_mov_b32_e32 v168, v162
	v_mov_b32_e32 v169, v163
	v_mov_b32_e32 v162, v156
	v_mov_b32_e32 v163, v157
	v_mov_b32_e32 v164, v158
	v_mov_b32_e32 v165, v159
	v_mov_b32_e32 v174, v152
	v_mov_b32_e32 v175, v153
	v_mov_b32_e32 v176, v154
	v_mov_b32_e32 v177, v155
	v_mov_b32_e32 v170, v148
	v_mov_b32_e32 v171, v149
	v_mov_b32_e32 v172, v150
	v_mov_b32_e32 v173, v151
	s_cmp_ge_i32 s72, s73
	s_mov_b64 s[0:1], -1
	s_cbranch_scc0 .LBB0_321

.LBB0_323:
	s_and_b32 s1, s79, 0x18000
	s_xor_b32 s0, s1, 0x10000
	v_add_u32_e32 v84, s0, v238
	v_add_u32_e32 v85, v84, v230
	v_add_u32_e32 v254, v84, v231
	v_add_u32_e32 v255, v84, v232
	v_add_u32_e32 v84, v84, v233
	ds_read_b128 v[80:83], v85 offset:16384
	ds_read_b128 v[202:205], v254 offset:16384
	ds_read_b128 v[194:197], v255 offset:16384
	ds_read_b128 v[186:189], v84 offset:16384
	ds_read_b128 v[198:201], v85 offset:20480
	ds_read_b128 v[190:193], v254 offset:20480
	ds_read_b128 v[246:249], v255 offset:20480
	ds_read_b128 v[250:253], v84 offset:20480
	s_cmp_ge_i32 s72, s98
	s_cbranch_scc1 .LBB0_325
	s_and_b32 s0, s79, 0x18000
	s_add_i32 m0, s0, s94
	s_add_i32 s1, s90, s0
	global_load_lds_dwordx4 v[220:221], off
	s_mov_b32 m0, s1
	s_add_i32 s1, s0, s66
	global_load_lds_dwordx4 v[218:219], off
	s_mov_b32 m0, s1
	v_lshl_add_u64 v[218:219], v[218:219], 0, s[88:89]
	global_load_lds_dwordx4 v[224:225], off
	global_load_lds_dwordx4 v[224:225], off offset:1024
	v_lshl_add_u64 v[220:221], v[220:221], 0, s[88:89]
	v_lshl_add_u64 v[224:225], v[224:225], 0, s[92:93]
.LBB0_325:
	s_waitcnt lgkmcnt(0)
	v_mfma_f32_32x32x16_bf16 v[96:111], v[80:83], v[144:147], v[64:79]
	v_mfma_f32_32x32x16_bf16 v[96:111], v[202:205], v[140:143], v[96:111]
	v_cvt_f32_i32_e32 v156, s100
	v_mfma_f32_32x32x16_bf16 v[96:111], v[194:197], v[136:139], v[96:111]
	v_fma_f32 v254, v208, v156, -v207
	v_mfma_f32_32x32x16_bf16 v[96:111], v[186:189], v[132:135], v[96:111]
	v_add_f32_e32 v255, v237, v254
	s_add_i32 s3, s79, 0xfffe8000
	s_and_b32 s3, s3, 0x18000
	v_add_u32_e32 v158, s3, v235
	v_add_u32_e32 v159, s3, v239
	v_add_u32_e32 v160, s3, v236
	v_add_u32_e32 v161, s3, v234
	ds_read_b64_tr_b16 v[182:183], v158 offset:32768
	ds_read_b64_tr_b16 v[184:185], v158 offset:34816
	ds_read_b64_tr_b16 v[178:179], v159 offset:32768
	ds_read_b64_tr_b16 v[180:181], v159 offset:34816
	ds_read_b64_tr_b16 v[148:149], v160 offset:32768
	ds_read_b64_tr_b16 v[150:151], v160 offset:34816
	ds_read_b64_tr_b16 v[152:153], v161 offset:32768
	ds_read_b64_tr_b16 v[154:155], v161 offset:34816
	v_mfma_f32_32x32x16_bf16 v[80:95], v[198:201], v[144:147], v[64:79]
	v_add_f32_e32 v96, v254, v96
	v_exp_f32_e32 v96, v96
	v_add_f32_e32 v97, v254, v97
	v_exp_f32_e32 v97, v97
	v_add_f32_e32 v98, v254, v98
	v_exp_f32_e32 v98, v98
	v_add_f32_e32 v99, v254, v99
	v_exp_f32_e32 v99, v99
	v_mfma_f32_32x32x16_bf16 v[80:95], v[190:193], v[140:143], v[80:95]
	v_add_f32_e32 v100, v254, v100
	v_exp_f32_e32 v100, v100
	v_add_f32_e32 v101, v254, v101
	v_exp_f32_e32 v101, v101
	v_add_f32_e32 v102, v254, v102
	v_exp_f32_e32 v102, v102
	v_add_f32_e32 v103, v254, v103
	v_exp_f32_e32 v103, v103
	v_mfma_f32_32x32x16_bf16 v[80:95], v[246:249], v[136:139], v[80:95]
	v_add_f32_e32 v104, v254, v104
	v_exp_f32_e32 v104, v104
	v_add_f32_e32 v105, v254, v105
	v_exp_f32_e32 v105, v105
	v_add_f32_e32 v106, v254, v106
	v_exp_f32_e32 v106, v106
	v_add_f32_e32 v107, v254, v107
	v_exp_f32_e32 v107, v107
	v_mfma_f32_32x32x16_bf16 v[80:95], v[250:253], v[132:135], v[80:95]
	v_add_f32_e32 v108, v254, v108
	v_exp_f32_e32 v108, v108
	v_add_f32_e32 v109, v254, v109
	v_exp_f32_e32 v109, v109
	v_add_f32_e32 v110, v254, v110
	v_exp_f32_e32 v110, v110
	v_add_f32_e32 v111, v254, v111
	v_exp_f32_e32 v111, v111
	s_cmp_le_i32 s97, s78
	s_cbranch_scc1 .LBB0_327
	s_lshl_b32 s4, s72, 6
	v_subrev_u32_e32 v156, s4, v240
	v_cmp_gt_i32_e64 s[60:61], 26, v156
	v_cmp_gt_i32_e64 s[62:63], 27, v156
	v_cmp_gt_i32_e64 s[58:59], 25, v156
	s_and_b64 s[60:61], s[62:63], s[60:61]
	v_cmp_gt_i32_e64 s[56:57], 24, v156
	s_and_b64 s[58:59], s[60:61], s[58:59]
	v_cmp_gt_i32_e64 s[54:55], 19, v156
	s_and_b64 s[56:57], s[58:59], s[56:57]
	v_cmp_gt_i32_e64 s[52:53], 18, v156
	s_and_b64 s[54:55], s[56:57], s[54:55]
	v_cmp_gt_i32_e64 s[50:51], 17, v156
	s_and_b64 s[52:53], s[54:55], s[52:53]
	v_cmp_gt_i32_e64 s[48:49], 16, v156
	s_and_b64 s[50:51], s[52:53], s[50:51]
	v_cmp_gt_i32_e64 s[46:47], 11, v156
	s_and_b64 s[48:49], s[50:51], s[48:49]
	v_cmp_gt_i32_e64 s[44:45], 10, v156
	s_and_b64 s[46:47], s[48:49], s[46:47]
	v_cmp_gt_i32_e64 s[42:43], 9, v156
	s_and_b64 s[44:45], s[46:47], s[44:45]
	v_cmp_gt_i32_e64 s[40:41], 8, v156
	s_and_b64 s[42:43], s[44:45], s[42:43]
	v_cmp_gt_i32_e64 s[38:39], 3, v156
	s_and_b64 s[40:41], s[42:43], s[40:41]
	v_cmp_gt_i32_e64 s[36:37], 2, v156
	s_and_b64 s[38:39], s[40:41], s[38:39]
	v_cmp_gt_i32_e64 s[34:35], 1, v156
	s_and_b64 s[36:37], s[38:39], s[36:37]
	v_cmp_gt_i32_e64 s[30:31], 0, v156
	s_and_b64 s[34:35], s[36:37], s[34:35]
	s_and_b64 s[30:31], s[34:35], s[30:31]
	v_cmp_gt_i32_e64 s[28:29], 58, v156
	v_cndmask_b32_e64 v96, v96, v113, s[30:31]
	v_cmp_gt_i32_e64 s[30:31], 59, v156
	v_cmp_gt_i32_e64 s[26:27], 57, v156
	s_and_b64 s[28:29], s[30:31], s[28:29]
	v_cmp_gt_i32_e64 s[24:25], 56, v156
	s_and_b64 s[26:27], s[28:29], s[26:27]
	v_cmp_gt_i32_e64 s[22:23], 51, v156
	s_and_b64 s[24:25], s[26:27], s[24:25]
	v_cmp_gt_i32_e64 s[20:21], 50, v156
	s_and_b64 s[22:23], s[24:25], s[22:23]
	v_cmp_gt_i32_e64 s[18:19], 49, v156
	s_and_b64 s[20:21], s[22:23], s[20:21]
	v_cmp_gt_i32_e64 s[16:17], 48, v156
	s_and_b64 s[18:19], s[20:21], s[18:19]
	v_cmp_gt_i32_e64 s[14:15], 43, v156
	s_and_b64 s[16:17], s[18:19], s[16:17]
	v_cmp_gt_i32_e64 s[12:13], 42, v156
	s_and_b64 s[14:15], s[16:17], s[14:15]
	v_cmp_gt_i32_e64 s[10:11], 41, v156
	s_and_b64 s[12:13], s[14:15], s[12:13]
	v_cmp_gt_i32_e64 s[8:9], 40, v156
	s_and_b64 s[10:11], s[12:13], s[10:11]
	v_cmp_gt_i32_e64 s[6:7], 35, v156
	s_and_b64 s[8:9], s[10:11], s[8:9]
	v_cmp_gt_i32_e64 s[4:5], 34, v156
	s_and_b64 s[6:7], s[8:9], s[6:7]
	v_cmp_gt_i32_e64 s[0:1], 33, v156
	s_and_b64 s[4:5], s[6:7], s[4:5]
	v_cmp_gt_i32_e32 vcc, 32, v156
	s_and_b64 s[0:1], s[4:5], s[0:1]
	s_and_b64 vcc, s[0:1], vcc
	v_cndmask_b32_e64 v111, v111, v113, s[62:63]
	v_cndmask_b32_e64 v110, v110, v113, s[60:61]
	v_cndmask_b32_e64 v109, v109, v113, s[58:59]
	v_cndmask_b32_e64 v108, v108, v113, s[56:57]
	v_cndmask_b32_e64 v107, v107, v113, s[54:55]
	v_cndmask_b32_e64 v106, v106, v113, s[52:53]
	v_cndmask_b32_e64 v105, v105, v113, s[50:51]
	v_cndmask_b32_e64 v104, v104, v113, s[48:49]
	v_cndmask_b32_e64 v103, v103, v113, s[46:47]
	v_cndmask_b32_e64 v102, v102, v113, s[44:45]
	v_cndmask_b32_e64 v101, v101, v113, s[42:43]
	v_cndmask_b32_e64 v100, v100, v113, s[40:41]
	v_cndmask_b32_e64 v99, v99, v113, s[38:39]
	v_cndmask_b32_e64 v98, v98, v113, s[36:37]
	v_cndmask_b32_e64 v97, v97, v113, s[34:35]
	v_cndmask_b32_e64 v95, v95, v228, s[30:31]
	v_cndmask_b32_e64 v94, v94, v228, s[28:29]
	v_cndmask_b32_e64 v93, v93, v228, s[26:27]
	v_cndmask_b32_e64 v92, v92, v228, s[24:25]
	v_cndmask_b32_e64 v91, v91, v228, s[22:23]
	v_cndmask_b32_e64 v90, v90, v228, s[20:21]
	v_cndmask_b32_e64 v89, v89, v228, s[18:19]
	v_cndmask_b32_e64 v88, v88, v228, s[16:17]
	v_cndmask_b32_e64 v87, v87, v228, s[14:15]
	v_cndmask_b32_e64 v86, v86, v228, s[12:13]
	v_cndmask_b32_e64 v85, v85, v228, s[10:11]
	v_cndmask_b32_e64 v84, v84, v228, s[8:9]
	v_cndmask_b32_e64 v83, v83, v228, s[6:7]
	v_cndmask_b32_e64 v82, v82, v228, s[4:5]
	v_cndmask_b32_e64 v81, v81, v228, s[0:1]
	v_cndmask_b32_e32 v80, v80, v228, vcc
.LBB0_327:
	s_waitcnt lgkmcnt(4)
	v_mfma_f32_32x32x16_bf16 v[48:63], v[182:185], v[174:177], v[48:63]
	v_add_f32_e32 v190, v255, v80
	v_exp_f32_e32 v190, v190
	ds_read_b64_tr_b16 v[246:247], v158 offset:36864
	ds_read_b64_tr_b16 v[248:249], v158 offset:38912
	v_add_f32_e32 v157, v190, v96
	v_mfma_f32_32x32x16_bf16 v[32:47], v[178:181], v[174:177], v[32:47]
	v_add_f32_e32 v191, v255, v81
	v_exp_f32_e32 v191, v191
	ds_read_b64_tr_b16 v[250:251], v159 offset:36864
	ds_read_b64_tr_b16 v[252:253], v159 offset:38912
	v_add_f32_e32 v156, v191, v97
	v_add_f32_e32 v157, v156, v157
	s_waitcnt lgkmcnt(4)
	v_mfma_f32_32x32x16_bf16 v[16:31], v[148:151], v[174:177], v[16:31]
	v_add_f32_e32 v192, v255, v82
	v_exp_f32_e32 v192, v192
	ds_read_b64_tr_b16 v[182:183], v160 offset:36864
	ds_read_b64_tr_b16 v[184:185], v160 offset:38912
	v_add_f32_e32 v156, v192, v98
	v_add_f32_e32 v157, v156, v157
	v_mfma_f32_32x32x16_bf16 v[0:15], v[152:155], v[174:177], v[0:15]
	v_add_f32_e32 v193, v255, v83
	v_exp_f32_e32 v193, v193
	ds_read_b64_tr_b16 v[178:179], v161 offset:36864
	ds_read_b64_tr_b16 v[180:181], v161 offset:38912
	v_add_f32_e32 v156, v193, v99
	v_add_f32_e32 v157, v156, v157
	v_cvt_pk_bf16_f32 v174, v96, v97
	s_waitcnt lgkmcnt(4)
	v_mfma_f32_32x32x16_bf16 v[48:63], v[246:249], v[162:165], v[48:63]
	v_add_f32_e32 v194, v255, v84
	v_exp_f32_e32 v194, v194
	ds_read_b64_tr_b16 v[148:149], v158 offset:40960
	ds_read_b64_tr_b16 v[150:151], v158 offset:43008
	v_add_f32_e32 v156, v194, v100
	v_add_f32_e32 v157, v156, v157
	v_cvt_pk_bf16_f32 v175, v98, v99
	v_mfma_f32_32x32x16_bf16 v[32:47], v[250:253], v[162:165], v[32:47]
	v_add_f32_e32 v195, v255, v85
	v_exp_f32_e32 v195, v195
	ds_read_b64_tr_b16 v[152:153], v159 offset:40960
	ds_read_b64_tr_b16 v[154:155], v159 offset:43008
	v_add_f32_e32 v156, v195, v101
	v_add_f32_e32 v157, v156, v157
	v_cvt_pk_bf16_f32 v176, v100, v101
	s_waitcnt lgkmcnt(4)
	v_mfma_f32_32x32x16_bf16 v[16:31], v[182:185], v[162:165], v[16:31]
	v_add_f32_e32 v196, v255, v86
	v_exp_f32_e32 v196, v196
	ds_read_b64_tr_b16 v[246:247], v160 offset:40960
	ds_read_b64_tr_b16 v[248:249], v160 offset:43008
	v_add_f32_e32 v156, v196, v102
	v_add_f32_e32 v157, v156, v157
	v_cvt_pk_bf16_f32 v177, v102, v103
	v_mfma_f32_32x32x16_bf16 v[0:15], v[178:181], v[162:165], v[0:15]
	v_add_f32_e32 v197, v255, v87
	v_exp_f32_e32 v197, v197
	ds_read_b64_tr_b16 v[250:251], v161 offset:40960
	ds_read_b64_tr_b16 v[252:253], v161 offset:43008
	v_add_f32_e32 v156, v197, v103
	v_add_f32_e32 v157, v156, v157
	v_cvt_pk_bf16_f32 v162, v104, v105
	s_waitcnt lgkmcnt(4)
	v_mfma_f32_32x32x16_bf16 v[48:63], v[148:151], v[170:173], v[48:63]
	v_add_f32_e32 v198, v255, v88
	v_exp_f32_e32 v198, v198
	ds_read_b64_tr_b16 v[182:183], v158 offset:45056
	ds_read_b64_tr_b16 v[184:185], v158 offset:47104
	v_add_f32_e32 v156, v198, v104
	v_add_f32_e32 v157, v156, v157
	v_cvt_pk_bf16_f32 v163, v106, v107
	v_mfma_f32_32x32x16_bf16 v[32:47], v[152:155], v[170:173], v[32:47]
	v_add_f32_e32 v199, v255, v89
	v_exp_f32_e32 v199, v199
	ds_read_b64_tr_b16 v[178:179], v159 offset:45056
	ds_read_b64_tr_b16 v[180:181], v159 offset:47104
	v_add_f32_e32 v156, v199, v105
	v_add_f32_e32 v157, v156, v157
	v_cvt_pk_bf16_f32 v164, v108, v109
	s_waitcnt lgkmcnt(4)
	v_mfma_f32_32x32x16_bf16 v[16:31], v[246:249], v[170:173], v[16:31]
	v_add_f32_e32 v200, v255, v90
	v_exp_f32_e32 v200, v200
	ds_read_b64_tr_b16 v[148:149], v160 offset:45056
	ds_read_b64_tr_b16 v[150:151], v160 offset:47104
	v_add_f32_e32 v156, v200, v106
	v_add_f32_e32 v157, v156, v157
	v_cvt_pk_bf16_f32 v165, v110, v111
	v_mfma_f32_32x32x16_bf16 v[0:15], v[250:253], v[170:173], v[0:15]
	v_add_f32_e32 v201, v255, v91
	v_exp_f32_e32 v201, v201
	ds_read_b64_tr_b16 v[152:153], v161 offset:45056
	ds_read_b64_tr_b16 v[154:155], v161 offset:47104
	v_add_f32_e32 v156, v201, v107
	v_add_f32_e32 v157, v156, v157
	v_cvt_pk_bf16_f32 v170, v190, v191
	s_waitcnt lgkmcnt(4)
	v_mfma_f32_32x32x16_bf16 v[48:63], v[182:185], v[166:169], v[48:63]
	v_add_f32_e32 v202, v255, v92
	v_exp_f32_e32 v202, v202
	v_cvt_pk_bf16_f32 v171, v192, v193
	v_add_f32_e32 v156, v202, v108
	v_add_f32_e32 v157, v156, v157
	v_mfma_f32_32x32x16_bf16 v[32:47], v[178:181], v[166:169], v[32:47]
	v_add_f32_e32 v203, v255, v93
	v_exp_f32_e32 v203, v203
	v_cvt_pk_bf16_f32 v172, v194, v195
	v_add_f32_e32 v156, v203, v109
	v_add_f32_e32 v157, v156, v157
	s_waitcnt lgkmcnt(0)
	v_mfma_f32_32x32x16_bf16 v[16:31], v[148:151], v[166:169], v[16:31]
	v_add_f32_e32 v204, v255, v94
	v_exp_f32_e32 v204, v204
	v_cvt_pk_bf16_f32 v173, v196, v197
	v_add_f32_e32 v156, v204, v110
	v_add_f32_e32 v157, v156, v157
	v_mfma_f32_32x32x16_bf16 v[0:15], v[152:155], v[166:169], v[0:15]
	v_add_f32_e32 v205, v255, v95
	v_exp_f32_e32 v205, v205
	v_cvt_pk_bf16_f32 v166, v198, v199
	v_add_f32_e32 v156, v205, v111
	v_add_f32_e32 v157, v156, v157
	v_cvt_pk_bf16_f32 v167, v200, v201
	v_cvt_pk_bf16_f32 v168, v202, v203
	v_cvt_pk_bf16_f32 v169, v204, v205
	s_add_i32 s72, s72, 1
	s_add_i32 s79, s79, 0x8000
	s_add_i32 s97, s97, 64
	s_add_i32 s100, s100, 64
	v_add_f32_e32 v229, v229, v157
	s_cmp_ge_i32 s72, s99
	s_cbranch_scc1 .LBB0_332
	s_cmp_ge_i32 s72, s73
	s_cbranch_scc1 .Lk_last
	s_waitcnt vmcnt(4) lgkmcnt(0)
	s_barrier
	s_branch .LBB0_323

	.amdhsa_kernel _Z8yoco_fwd6Params
		.amdhsa_group_segment_fixed_size 0
		.amdhsa_private_segment_fixed_size 0
		.amdhsa_kernarg_size 488
		.amdhsa_user_sgpr_count 2
		.amdhsa_user_sgpr_dispatch_ptr 0
		.amdhsa_user_sgpr_queue_ptr 0
		.amdhsa_user_sgpr_kernarg_segment_ptr 1
		.amdhsa_user_sgpr_dispatch_id 0
		.amdhsa_user_sgpr_kernarg_preload_length 0
		.amdhsa_user_sgpr_kernarg_preload_offset 0
		.amdhsa_user_sgpr_private_segment_size 0
		.amdhsa_uses_dynamic_stack 0
		.amdhsa_enable_private_segment 0
		.amdhsa_system_sgpr_workgroup_id_x 1
		.amdhsa_system_sgpr_workgroup_id_y 0
		.amdhsa_system_sgpr_workgroup_id_z 0
		.amdhsa_system_sgpr_workgroup_info 0
		.amdhsa_system_vgpr_workitem_id 2
		.amdhsa_next_free_vgpr 256
		.amdhsa_next_free_sgpr 102
		.amdhsa_accum_offset 256
		.amdhsa_reserve_vcc 1
		.amdhsa_float_round_mode_32 0
		.amdhsa_float_round_mode_16_64 0
		.amdhsa_float_denorm_mode_32 3
		.amdhsa_float_denorm_mode_16_64 3
		.amdhsa_dx10_clamp 1
		.amdhsa_ieee_mode 1
		.amdhsa_fp16_overflow 0
		.amdhsa_tg_split 0
		.amdhsa_exception_fp_ieee_invalid_op 0
		.amdhsa_exception_fp_denorm_src 0
		.amdhsa_exception_fp_ieee_div_zero 0
		.amdhsa_exception_fp_ieee_overflow 0
		.amdhsa_exception_fp_ieee_underflow 0
		.amdhsa_exception_fp_ieee_inexact 0
		.amdhsa_exception_int_div_zero 0
	.end_amdhsa_kernel

amdhsa.kernels:
  - .agpr_count:     0
    .args:
      - .offset:         0
        .size:           232
        .value_kind:     by_value
      - .offset:         232
        .size:           4
        .value_kind:     hidden_block_count_x
      - .offset:         236
        .size:           4
        .value_kind:     hidden_block_count_y
      - .offset:         240
        .size:           4
        .value_kind:     hidden_block_count_z
      - .offset:         244
        .size:           2
        .value_kind:     hidden_group_size_x
      - .offset:         246
        .size:           2
        .value_kind:     hidden_group_size_y
      - .offset:         248
        .size:           2
        .value_kind:     hidden_group_size_z
      - .offset:         250
        .size:           2
        .value_kind:     hidden_remainder_x
      - .offset:         252
        .size:           2
        .value_kind:     hidden_remainder_y
      - .offset:         254
        .size:           2
        .value_kind:     hidden_remainder_z
      - .offset:         272
        .size:           8
        .value_kind:     hidden_global_offset_x
      - .offset:         280
        .size:           8
        .value_kind:     hidden_global_offset_y
      - .offset:         288
        .size:           8
        .value_kind:     hidden_global_offset_z
      - .offset:         296
        .size:           2
        .value_kind:     hidden_grid_dims
      - .offset:         320
        .size:           8
        .value_kind:     hidden_multigrid_sync_arg
      - .offset:         352
        .size:           4
        .value_kind:     hidden_dynamic_lds_size
    .group_segment_fixed_size: 0
    .kernarg_segment_align: 8
    .kernarg_segment_size: 488
    .language:       OpenCL C
    .language_version:
      - 2
      - 0
    .max_flat_workgroup_size: 512
    .name:           _Z8yoco_fwd6Params
    .private_segment_fixed_size: 0
    .sgpr_count:     108
    .sgpr_spill_count: 97
    .symbol:         _Z8yoco_fwd6Params.kd
    .uniform_work_group_size: 1
    .uses_dynamic_stack: false
    .vgpr_count:     256
    .vgpr_spill_count: 0
    .wavefront_size: 64
